# v81 + phase 4a epilogue: the 8 sb gate rows of each half requested up front (counted waits) instead of load/wait/store per row
# speedup vs baseline: 1.0210x; 1.0033x over previous
.LBB0_552:
	s_or_b64 exec, exec, s[2:3]
	s_mov_b64 s[2:3], -1
	s_and_b64 vcc, exec, s[42:43]
	v_add_u32_e32 v145, 0x400, v219
	v_add_u32_e32 v144, 0x800, v219
	v_add_u32_e32 v143, 0xc00, v219
	v_add_u32_e32 v142, 0x4000, v219
	v_add_u32_e32 v141, 0x4400, v219
	v_add_u32_e32 v140, 0x4800, v219
	v_add_u32_e32 v139, 0x4c00, v219
	v_add_u32_e32 v147, 0x8000, v219
	v_add_u32_e32 v138, 0x8400, v219
	v_add_u32_e32 v136, 0x8800, v219
	v_add_u32_e32 v135, 0x8c00, v219
	v_add_u32_e32 v146, 0xc000, v219
	v_add_u32_e32 v134, 0xc400, v219
	v_add_u32_e32 v133, 0xc800, v219
	v_add_u32_e32 v132, 0xcc00, v219
	v_add_u32_e32 v137, 0x9000, v219
	v_add_u32_e32 v0, 0xd000, v219
	s_waitcnt vmcnt(0) lgkmcnt(0)
	s_cbranch_vccz .LBB0_559
	s_mov_b32 s2, 0
	v_mov_b32_e32 v2, v225
	s_barrier
	ds_write2_b32 v219, v68, v72 offset1:16
	ds_write2_b32 v145, v69, v73 offset0:4 offset1:20
	ds_write2_b32 v144, v70, v74 offset0:8 offset1:24
	ds_write2_b32 v143, v71, v75 offset0:12 offset1:28
	ds_write2_b32 v142, v76, v80 offset0:64 offset1:80
	ds_write2_b32 v141, v77, v81 offset0:68 offset1:84
	ds_write2_b32 v140, v78, v82 offset0:72 offset1:88
	ds_write2_b32 v139, v79, v83 offset0:76 offset1:92
	ds_write2_b32 v147, v84, v88 offset0:128 offset1:144
	ds_write2_b32 v138, v85, v89 offset0:132 offset1:148
	ds_write2_b32 v136, v86, v90 offset0:136 offset1:152
	ds_write2_b32 v135, v87, v91 offset0:140 offset1:156
	ds_write2_b32 v146, v92, v96 offset0:192 offset1:208
	ds_write2_b32 v134, v93, v97 offset0:196 offset1:212
	ds_write2_b32 v133, v94, v98 offset0:200 offset1:216
	ds_write2_b32 v132, v95, v99 offset0:204 offset1:220
	ds_write2_b32 v219, v100, v104 offset0:128 offset1:144
	ds_write2_b32 v145, v101, v105 offset0:132 offset1:148
	ds_write2_b32 v144, v102, v106 offset0:136 offset1:152
	ds_write2_b32 v143, v103, v107 offset0:140 offset1:156
	ds_write2_b32 v142, v108, v112 offset0:192 offset1:208
	ds_write2_b32 v141, v109, v113 offset0:196 offset1:212
	ds_write2_b32 v140, v110, v114 offset0:200 offset1:216
	ds_write2_b32 v139, v111, v115 offset0:204 offset1:220
	ds_write2_b32 v138, v116, v120 offset1:16
	ds_write2_b32 v136, v117, v121 offset0:4 offset1:20
	ds_write2_b32 v135, v118, v122 offset0:8 offset1:24
	ds_write2_b32 v137, v119, v123 offset0:12 offset1:28
	ds_write2_b32 v134, v124, v128 offset0:64 offset1:80
	ds_write2_b32 v133, v125, v129 offset0:68 offset1:84
	ds_write2_b32 v132, v126, v130 offset0:72 offset1:88
	ds_write2_b32 v0, v127, v131 offset0:76 offset1:92
	s_waitcnt lgkmcnt(0)
	s_barrier
	v_add_u32_e32 v236, 0, v2
	v_ashrrev_i32_e32 v237, 31, v236
	v_lshlrev_b64 v[236:237], 10, v[236:237]
	v_lshl_add_u64 v[236:237], v[236:237], 0, v[198:199]
	v_lshlrev_b64 v[236:237], 1, v[236:237]
	v_lshl_add_u64 v[236:237], s[8:9], 0, v[236:237]
	global_load_dwordx4 v[148:151], v[236:237], off
	v_add_u32_e32 v236, 4, v2
	v_ashrrev_i32_e32 v237, 31, v236
	v_lshlrev_b64 v[236:237], 10, v[236:237]
	v_lshl_add_u64 v[236:237], v[236:237], 0, v[198:199]
	v_lshlrev_b64 v[236:237], 1, v[236:237]
	v_lshl_add_u64 v[236:237], s[8:9], 0, v[236:237]
	global_load_dwordx4 v[152:155], v[236:237], off
	v_add_u32_e32 v236, 8, v2
	v_ashrrev_i32_e32 v237, 31, v236
	v_lshlrev_b64 v[236:237], 10, v[236:237]
	v_lshl_add_u64 v[236:237], v[236:237], 0, v[198:199]
	v_lshlrev_b64 v[236:237], 1, v[236:237]
	v_lshl_add_u64 v[236:237], s[8:9], 0, v[236:237]
	global_load_dwordx4 v[156:159], v[236:237], off
	v_add_u32_e32 v236, 12, v2
	v_ashrrev_i32_e32 v237, 31, v236
	v_lshlrev_b64 v[236:237], 10, v[236:237]
	v_lshl_add_u64 v[236:237], v[236:237], 0, v[198:199]
	v_lshlrev_b64 v[236:237], 1, v[236:237]
	v_lshl_add_u64 v[236:237], s[8:9], 0, v[236:237]
	global_load_dwordx4 v[160:163], v[236:237], off
	v_add_u32_e32 v236, 16, v2
	v_ashrrev_i32_e32 v237, 31, v236
	v_lshlrev_b64 v[236:237], 10, v[236:237]
	v_lshl_add_u64 v[236:237], v[236:237], 0, v[198:199]
	v_lshlrev_b64 v[236:237], 1, v[236:237]
	v_lshl_add_u64 v[236:237], s[8:9], 0, v[236:237]
	global_load_dwordx4 v[164:167], v[236:237], off
	v_add_u32_e32 v236, 20, v2
	v_ashrrev_i32_e32 v237, 31, v236
	v_lshlrev_b64 v[236:237], 10, v[236:237]
	v_lshl_add_u64 v[236:237], v[236:237], 0, v[198:199]
	v_lshlrev_b64 v[236:237], 1, v[236:237]
	v_lshl_add_u64 v[236:237], s[8:9], 0, v[236:237]
	global_load_dwordx4 v[168:171], v[236:237], off
	v_add_u32_e32 v236, 24, v2
	v_ashrrev_i32_e32 v237, 31, v236
	v_lshlrev_b64 v[236:237], 10, v[236:237]
	v_lshl_add_u64 v[236:237], v[236:237], 0, v[198:199]
	v_lshlrev_b64 v[236:237], 1, v[236:237]
	v_lshl_add_u64 v[236:237], s[8:9], 0, v[236:237]
	global_load_dwordx4 v[172:175], v[236:237], off
	v_add_u32_e32 v236, 28, v2
	v_ashrrev_i32_e32 v237, 31, v236
	v_lshlrev_b64 v[236:237], 10, v[236:237]
	v_lshl_add_u64 v[236:237], v[236:237], 0, v[198:199]
	v_lshlrev_b64 v[236:237], 1, v[236:237]
	v_lshl_add_u64 v[236:237], s[8:9], 0, v[236:237]
	global_load_dwordx4 v[176:179], v[236:237], off
	ds_read_b128 v[180:183], v221 offset:0
	ds_read_b128 v[184:187], v221 offset:16
	v_add_u32_e32 v238, 0, v2
	v_ashrrev_i32_e32 v239, 31, v238
	v_lshlrev_b64 v[238:239], 10, v[238:239]
	v_lshl_add_u64 v[238:239], v[238:239], 0, v[198:199]
	v_lshlrev_b64 v[238:239], 1, v[238:239]
	v_lshl_add_u64 v[238:239], s[38:39], 0, v[238:239]
	s_waitcnt vmcnt(7)
	v_lshlrev_b32_e32 v200, 16, v148
	v_and_b32_e32 v201, 0xffff0000, v148
	v_lshlrev_b32_e32 v202, 16, v149
	v_and_b32_e32 v203, 0xffff0000, v149
	v_lshlrev_b32_e32 v204, 16, v150
	v_and_b32_e32 v205, 0xffff0000, v150
	v_lshlrev_b32_e32 v206, 16, v151
	v_and_b32_e32 v207, 0xffff0000, v151
	v_max_f32_e32 v200, v200, v200
	v_max_f32_e32 v201, v201, v201
	v_max_f32_e32 v202, v202, v202
	v_max_f32_e32 v203, v203, v203
	v_max_f32_e32 v204, v204, v204
	v_max_f32_e32 v205, v205, v205
	v_max_f32_e32 v206, v206, v206
	v_max_f32_e32 v207, v207, v207
	v_max_f32_e32 v200, 0xda24260, v200
	v_max_f32_e32 v201, 0xda24260, v201
	v_max_f32_e32 v202, 0xda24260, v202
	v_max_f32_e32 v203, 0xda24260, v203
	v_max_f32_e32 v204, 0xda24260, v204
	v_max_f32_e32 v205, 0xda24260, v205
	v_max_f32_e32 v206, 0xda24260, v206
	v_max_f32_e32 v207, 0xda24260, v207
	s_waitcnt lgkmcnt(0)
	v_pk_mul_f32 v[180:181], v[180:181], v[200:201]
	v_pk_mul_f32 v[182:183], v[182:183], v[202:203]
	v_pk_mul_f32 v[184:185], v[184:185], v[204:205]
	v_pk_mul_f32 v[186:187], v[186:187], v[206:207]
	v_cvt_pk_bf16_f32 v180, v180, v181
	v_cvt_pk_bf16_f32 v181, v182, v183
	v_cvt_pk_bf16_f32 v182, v184, v185
	v_cvt_pk_bf16_f32 v183, v186, v187
	global_store_dwordx4 v[238:239], v[180:183], off
	ds_read_b128 v[188:191], v221 offset:4160
	ds_read_b128 v[192:195], v221 offset:4176
	v_add_u32_e32 v240, 4, v2
	v_ashrrev_i32_e32 v241, 31, v240
	v_lshlrev_b64 v[240:241], 10, v[240:241]
	v_lshl_add_u64 v[240:241], v[240:241], 0, v[198:199]
	v_lshlrev_b64 v[240:241], 1, v[240:241]
	v_lshl_add_u64 v[240:241], s[38:39], 0, v[240:241]
	s_waitcnt vmcnt(7)
	v_lshlrev_b32_e32 v228, 16, v152
	v_and_b32_e32 v229, 0xffff0000, v152
	v_lshlrev_b32_e32 v230, 16, v153
	v_and_b32_e32 v231, 0xffff0000, v153
	v_lshlrev_b32_e32 v232, 16, v154
	v_and_b32_e32 v233, 0xffff0000, v154
	v_lshlrev_b32_e32 v234, 16, v155
	v_and_b32_e32 v235, 0xffff0000, v155
	v_max_f32_e32 v228, v228, v228
	v_max_f32_e32 v229, v229, v229
	v_max_f32_e32 v230, v230, v230
	v_max_f32_e32 v231, v231, v231
	v_max_f32_e32 v232, v232, v232
	v_max_f32_e32 v233, v233, v233
	v_max_f32_e32 v234, v234, v234
	v_max_f32_e32 v235, v235, v235
	v_max_f32_e32 v228, 0xda24260, v228
	v_max_f32_e32 v229, 0xda24260, v229
	v_max_f32_e32 v230, 0xda24260, v230
	v_max_f32_e32 v231, 0xda24260, v231
	v_max_f32_e32 v232, 0xda24260, v232
	v_max_f32_e32 v233, 0xda24260, v233
	v_max_f32_e32 v234, 0xda24260, v234
	v_max_f32_e32 v235, 0xda24260, v235
	s_waitcnt lgkmcnt(0)
	v_pk_mul_f32 v[188:189], v[188:189], v[228:229]
	v_pk_mul_f32 v[190:191], v[190:191], v[230:231]
	v_pk_mul_f32 v[192:193], v[192:193], v[232:233]
	v_pk_mul_f32 v[194:195], v[194:195], v[234:235]
	v_cvt_pk_bf16_f32 v188, v188, v189
	v_cvt_pk_bf16_f32 v189, v190, v191
	v_cvt_pk_bf16_f32 v190, v192, v193
	v_cvt_pk_bf16_f32 v191, v194, v195
	global_store_dwordx4 v[240:241], v[188:191], off
	ds_read_b128 v[180:183], v221 offset:8320
	ds_read_b128 v[184:187], v221 offset:8336
	v_add_u32_e32 v238, 8, v2
	v_ashrrev_i32_e32 v239, 31, v238
	v_lshlrev_b64 v[238:239], 10, v[238:239]
	v_lshl_add_u64 v[238:239], v[238:239], 0, v[198:199]
	v_lshlrev_b64 v[238:239], 1, v[238:239]
	v_lshl_add_u64 v[238:239], s[38:39], 0, v[238:239]
	s_waitcnt vmcnt(7)
	v_lshlrev_b32_e32 v200, 16, v156
	v_and_b32_e32 v201, 0xffff0000, v156
	v_lshlrev_b32_e32 v202, 16, v157
	v_and_b32_e32 v203, 0xffff0000, v157
	v_lshlrev_b32_e32 v204, 16, v158
	v_and_b32_e32 v205, 0xffff0000, v158
	v_lshlrev_b32_e32 v206, 16, v159
	v_and_b32_e32 v207, 0xffff0000, v159
	v_max_f32_e32 v200, v200, v200
	v_max_f32_e32 v201, v201, v201
	v_max_f32_e32 v202, v202, v202
	v_max_f32_e32 v203, v203, v203
	v_max_f32_e32 v204, v204, v204
	v_max_f32_e32 v205, v205, v205
	v_max_f32_e32 v206, v206, v206
	v_max_f32_e32 v207, v207, v207
	v_max_f32_e32 v200, 0xda24260, v200
	v_max_f32_e32 v201, 0xda24260, v201
	v_max_f32_e32 v202, 0xda24260, v202
	v_max_f32_e32 v203, 0xda24260, v203
	v_max_f32_e32 v204, 0xda24260, v204
	v_max_f32_e32 v205, 0xda24260, v205
	v_max_f32_e32 v206, 0xda24260, v206
	v_max_f32_e32 v207, 0xda24260, v207
	s_waitcnt lgkmcnt(0)
	v_pk_mul_f32 v[180:181], v[180:181], v[200:201]
	v_pk_mul_f32 v[182:183], v[182:183], v[202:203]
	v_pk_mul_f32 v[184:185], v[184:185], v[204:205]
	v_pk_mul_f32 v[186:187], v[186:187], v[206:207]
	v_cvt_pk_bf16_f32 v180, v180, v181
	v_cvt_pk_bf16_f32 v181, v182, v183
	v_cvt_pk_bf16_f32 v182, v184, v185
	v_cvt_pk_bf16_f32 v183, v186, v187
	global_store_dwordx4 v[238:239], v[180:183], off
	ds_read_b128 v[188:191], v221 offset:12480
	ds_read_b128 v[192:195], v221 offset:12496
	v_add_u32_e32 v240, 12, v2
	v_ashrrev_i32_e32 v241, 31, v240
	v_lshlrev_b64 v[240:241], 10, v[240:241]
	v_lshl_add_u64 v[240:241], v[240:241], 0, v[198:199]
	v_lshlrev_b64 v[240:241], 1, v[240:241]
	v_lshl_add_u64 v[240:241], s[38:39], 0, v[240:241]
	s_waitcnt vmcnt(7)
	v_lshlrev_b32_e32 v228, 16, v160
	v_and_b32_e32 v229, 0xffff0000, v160
	v_lshlrev_b32_e32 v230, 16, v161
	v_and_b32_e32 v231, 0xffff0000, v161
	v_lshlrev_b32_e32 v232, 16, v162
	v_and_b32_e32 v233, 0xffff0000, v162
	v_lshlrev_b32_e32 v234, 16, v163
	v_and_b32_e32 v235, 0xffff0000, v163
	v_max_f32_e32 v228, v228, v228
	v_max_f32_e32 v229, v229, v229
	v_max_f32_e32 v230, v230, v230
	v_max_f32_e32 v231, v231, v231
	v_max_f32_e32 v232, v232, v232
	v_max_f32_e32 v233, v233, v233
	v_max_f32_e32 v234, v234, v234
	v_max_f32_e32 v235, v235, v235
	v_max_f32_e32 v228, 0xda24260, v228
	v_max_f32_e32 v229, 0xda24260, v229
	v_max_f32_e32 v230, 0xda24260, v230
	v_max_f32_e32 v231, 0xda24260, v231
	v_max_f32_e32 v232, 0xda24260, v232
	v_max_f32_e32 v233, 0xda24260, v233
	v_max_f32_e32 v234, 0xda24260, v234
	v_max_f32_e32 v235, 0xda24260, v235
	s_waitcnt lgkmcnt(0)
	v_pk_mul_f32 v[188:189], v[188:189], v[228:229]
	v_pk_mul_f32 v[190:191], v[190:191], v[230:231]
	v_pk_mul_f32 v[192:193], v[192:193], v[232:233]
	v_pk_mul_f32 v[194:195], v[194:195], v[234:235]
	v_cvt_pk_bf16_f32 v188, v188, v189
	v_cvt_pk_bf16_f32 v189, v190, v191
	v_cvt_pk_bf16_f32 v190, v192, v193
	v_cvt_pk_bf16_f32 v191, v194, v195
	global_store_dwordx4 v[240:241], v[188:191], off
	ds_read_b128 v[180:183], v221 offset:16640
	ds_read_b128 v[184:187], v221 offset:16656
	v_add_u32_e32 v238, 16, v2
	v_ashrrev_i32_e32 v239, 31, v238
	v_lshlrev_b64 v[238:239], 10, v[238:239]
	v_lshl_add_u64 v[238:239], v[238:239], 0, v[198:199]
	v_lshlrev_b64 v[238:239], 1, v[238:239]
	v_lshl_add_u64 v[238:239], s[38:39], 0, v[238:239]
	s_waitcnt vmcnt(7)
	v_lshlrev_b32_e32 v200, 16, v164
	v_and_b32_e32 v201, 0xffff0000, v164
	v_lshlrev_b32_e32 v202, 16, v165
	v_and_b32_e32 v203, 0xffff0000, v165
	v_lshlrev_b32_e32 v204, 16, v166
	v_and_b32_e32 v205, 0xffff0000, v166
	v_lshlrev_b32_e32 v206, 16, v167
	v_and_b32_e32 v207, 0xffff0000, v167
	v_max_f32_e32 v200, v200, v200
	v_max_f32_e32 v201, v201, v201
	v_max_f32_e32 v202, v202, v202
	v_max_f32_e32 v203, v203, v203
	v_max_f32_e32 v204, v204, v204
	v_max_f32_e32 v205, v205, v205
	v_max_f32_e32 v206, v206, v206
	v_max_f32_e32 v207, v207, v207
	v_max_f32_e32 v200, 0xda24260, v200
	v_max_f32_e32 v201, 0xda24260, v201
	v_max_f32_e32 v202, 0xda24260, v202
	v_max_f32_e32 v203, 0xda24260, v203
	v_max_f32_e32 v204, 0xda24260, v204
	v_max_f32_e32 v205, 0xda24260, v205
	v_max_f32_e32 v206, 0xda24260, v206
	v_max_f32_e32 v207, 0xda24260, v207
	s_waitcnt lgkmcnt(0)
	v_pk_mul_f32 v[180:181], v[180:181], v[200:201]
	v_pk_mul_f32 v[182:183], v[182:183], v[202:203]
	v_pk_mul_f32 v[184:185], v[184:185], v[204:205]
	v_pk_mul_f32 v[186:187], v[186:187], v[206:207]
	v_cvt_pk_bf16_f32 v180, v180, v181
	v_cvt_pk_bf16_f32 v181, v182, v183
	v_cvt_pk_bf16_f32 v182, v184, v185
	v_cvt_pk_bf16_f32 v183, v186, v187
	global_store_dwordx4 v[238:239], v[180:183], off
	ds_read_b128 v[188:191], v221 offset:20800
	ds_read_b128 v[192:195], v221 offset:20816
	v_add_u32_e32 v240, 20, v2
	v_ashrrev_i32_e32 v241, 31, v240
	v_lshlrev_b64 v[240:241], 10, v[240:241]
	v_lshl_add_u64 v[240:241], v[240:241], 0, v[198:199]
	v_lshlrev_b64 v[240:241], 1, v[240:241]
	v_lshl_add_u64 v[240:241], s[38:39], 0, v[240:241]
	s_waitcnt vmcnt(7)
	v_lshlrev_b32_e32 v228, 16, v168
	v_and_b32_e32 v229, 0xffff0000, v168
	v_lshlrev_b32_e32 v230, 16, v169
	v_and_b32_e32 v231, 0xffff0000, v169
	v_lshlrev_b32_e32 v232, 16, v170
	v_and_b32_e32 v233, 0xffff0000, v170
	v_lshlrev_b32_e32 v234, 16, v171
	v_and_b32_e32 v235, 0xffff0000, v171
	v_max_f32_e32 v228, v228, v228
	v_max_f32_e32 v229, v229, v229
	v_max_f32_e32 v230, v230, v230
	v_max_f32_e32 v231, v231, v231
	v_max_f32_e32 v232, v232, v232
	v_max_f32_e32 v233, v233, v233
	v_max_f32_e32 v234, v234, v234
	v_max_f32_e32 v235, v235, v235
	v_max_f32_e32 v228, 0xda24260, v228
	v_max_f32_e32 v229, 0xda24260, v229
	v_max_f32_e32 v230, 0xda24260, v230
	v_max_f32_e32 v231, 0xda24260, v231
	v_max_f32_e32 v232, 0xda24260, v232
	v_max_f32_e32 v233, 0xda24260, v233
	v_max_f32_e32 v234, 0xda24260, v234
	v_max_f32_e32 v235, 0xda24260, v235
	s_waitcnt lgkmcnt(0)
	v_pk_mul_f32 v[188:189], v[188:189], v[228:229]
	v_pk_mul_f32 v[190:191], v[190:191], v[230:231]
	v_pk_mul_f32 v[192:193], v[192:193], v[232:233]
	v_pk_mul_f32 v[194:195], v[194:195], v[234:235]
	v_cvt_pk_bf16_f32 v188, v188, v189
	v_cvt_pk_bf16_f32 v189, v190, v191
	v_cvt_pk_bf16_f32 v190, v192, v193
	v_cvt_pk_bf16_f32 v191, v194, v195
	global_store_dwordx4 v[240:241], v[188:191], off
	ds_read_b128 v[180:183], v221 offset:24960
	ds_read_b128 v[184:187], v221 offset:24976
	v_add_u32_e32 v238, 24, v2
	v_ashrrev_i32_e32 v239, 31, v238
	v_lshlrev_b64 v[238:239], 10, v[238:239]
	v_lshl_add_u64 v[238:239], v[238:239], 0, v[198:199]
	v_lshlrev_b64 v[238:239], 1, v[238:239]
	v_lshl_add_u64 v[238:239], s[38:39], 0, v[238:239]
	s_waitcnt vmcnt(7)
	v_lshlrev_b32_e32 v200, 16, v172
	v_and_b32_e32 v201, 0xffff0000, v172
	v_lshlrev_b32_e32 v202, 16, v173
	v_and_b32_e32 v203, 0xffff0000, v173
	v_lshlrev_b32_e32 v204, 16, v174
	v_and_b32_e32 v205, 0xffff0000, v174
	v_lshlrev_b32_e32 v206, 16, v175
	v_and_b32_e32 v207, 0xffff0000, v175
	v_max_f32_e32 v200, v200, v200
	v_max_f32_e32 v201, v201, v201
	v_max_f32_e32 v202, v202, v202
	v_max_f32_e32 v203, v203, v203
	v_max_f32_e32 v204, v204, v204
	v_max_f32_e32 v205, v205, v205
	v_max_f32_e32 v206, v206, v206
	v_max_f32_e32 v207, v207, v207
	v_max_f32_e32 v200, 0xda24260, v200
	v_max_f32_e32 v201, 0xda24260, v201
	v_max_f32_e32 v202, 0xda24260, v202
	v_max_f32_e32 v203, 0xda24260, v203
	v_max_f32_e32 v204, 0xda24260, v204
	v_max_f32_e32 v205, 0xda24260, v205
	v_max_f32_e32 v206, 0xda24260, v206
	v_max_f32_e32 v207, 0xda24260, v207
	s_waitcnt lgkmcnt(0)
	v_pk_mul_f32 v[180:181], v[180:181], v[200:201]
	v_pk_mul_f32 v[182:183], v[182:183], v[202:203]
	v_pk_mul_f32 v[184:185], v[184:185], v[204:205]
	v_pk_mul_f32 v[186:187], v[186:187], v[206:207]
	v_cvt_pk_bf16_f32 v180, v180, v181
	v_cvt_pk_bf16_f32 v181, v182, v183
	v_cvt_pk_bf16_f32 v182, v184, v185
	v_cvt_pk_bf16_f32 v183, v186, v187
	global_store_dwordx4 v[238:239], v[180:183], off
	ds_read_b128 v[188:191], v221 offset:29120
	ds_read_b128 v[192:195], v221 offset:29136
	v_add_u32_e32 v240, 28, v2
	v_ashrrev_i32_e32 v241, 31, v240
	v_lshlrev_b64 v[240:241], 10, v[240:241]
	v_lshl_add_u64 v[240:241], v[240:241], 0, v[198:199]
	v_lshlrev_b64 v[240:241], 1, v[240:241]
	v_lshl_add_u64 v[240:241], s[38:39], 0, v[240:241]
	s_waitcnt vmcnt(7)
	v_lshlrev_b32_e32 v228, 16, v176
	v_and_b32_e32 v229, 0xffff0000, v176
	v_lshlrev_b32_e32 v230, 16, v177
	v_and_b32_e32 v231, 0xffff0000, v177
	v_lshlrev_b32_e32 v232, 16, v178
	v_and_b32_e32 v233, 0xffff0000, v178
	v_lshlrev_b32_e32 v234, 16, v179
	v_and_b32_e32 v235, 0xffff0000, v179
	v_max_f32_e32 v228, v228, v228
	v_max_f32_e32 v229, v229, v229
	v_max_f32_e32 v230, v230, v230
	v_max_f32_e32 v231, v231, v231
	v_max_f32_e32 v232, v232, v232
	v_max_f32_e32 v233, v233, v233
	v_max_f32_e32 v234, v234, v234
	v_max_f32_e32 v235, v235, v235
	v_max_f32_e32 v228, 0xda24260, v228
	v_max_f32_e32 v229, 0xda24260, v229
	v_max_f32_e32 v230, 0xda24260, v230
	v_max_f32_e32 v231, 0xda24260, v231
	v_max_f32_e32 v232, 0xda24260, v232
	v_max_f32_e32 v233, 0xda24260, v233
	v_max_f32_e32 v234, 0xda24260, v234
	v_max_f32_e32 v235, 0xda24260, v235
	s_waitcnt lgkmcnt(0)
	v_pk_mul_f32 v[188:189], v[188:189], v[228:229]
	v_pk_mul_f32 v[190:191], v[190:191], v[230:231]
	v_pk_mul_f32 v[192:193], v[192:193], v[232:233]
	v_pk_mul_f32 v[194:195], v[194:195], v[234:235]
	v_cvt_pk_bf16_f32 v188, v188, v189
	v_cvt_pk_bf16_f32 v189, v190, v191
	v_cvt_pk_bf16_f32 v190, v192, v193
	v_cvt_pk_bf16_f32 v191, v194, v195
	global_store_dwordx4 v[240:241], v[188:191], off
	s_andn2_b64 vcc, exec, s[24:25]
	s_cbranch_vccnz .LBB0_558
	s_waitcnt lgkmcnt(0)
	s_mov_b32 s2, 0
	v_mov_b32_e32 v2, v226
	s_barrier
	ds_write2_b32 v219, v8, v4 offset1:16
	ds_write2_b32 v145, v9, v5 offset0:4 offset1:20
	ds_write2_b32 v144, v10, v6 offset0:8 offset1:24
	ds_write2_b32 v143, v11, v7 offset0:12 offset1:28
	ds_write2_b32 v142, v16, v12 offset0:64 offset1:80
	ds_write2_b32 v141, v17, v13 offset0:68 offset1:84
	ds_write2_b32 v140, v18, v14 offset0:72 offset1:88
	ds_write2_b32 v139, v19, v15 offset0:76 offset1:92
	ds_write2_b32 v147, v24, v20 offset0:128 offset1:144
	ds_write2_b32 v138, v25, v21 offset0:132 offset1:148
	ds_write2_b32 v136, v26, v22 offset0:136 offset1:152
	ds_write2_b32 v135, v27, v23 offset0:140 offset1:156
	ds_write2_b32 v146, v32, v28 offset0:192 offset1:208
	ds_write2_b32 v134, v33, v29 offset0:196 offset1:212
	ds_write2_b32 v133, v34, v30 offset0:200 offset1:216
	ds_write2_b32 v132, v35, v31 offset0:204 offset1:220
	ds_write2_b32 v219, v40, v36 offset0:128 offset1:144
	ds_write2_b32 v145, v41, v37 offset0:132 offset1:148
	ds_write2_b32 v144, v42, v38 offset0:136 offset1:152
	ds_write2_b32 v143, v43, v39 offset0:140 offset1:156
	ds_write2_b32 v142, v48, v44 offset0:192 offset1:208
	ds_write2_b32 v141, v49, v45 offset0:196 offset1:212
	ds_write2_b32 v140, v50, v46 offset0:200 offset1:216
	ds_write2_b32 v139, v51, v47 offset0:204 offset1:220
	ds_write2_b32 v138, v56, v52 offset1:16
	ds_write2_b32 v136, v57, v53 offset0:4 offset1:20
	ds_write2_b32 v135, v58, v54 offset0:8 offset1:24
	ds_write2_b32 v137, v59, v55 offset0:12 offset1:28
	ds_write2_b32 v134, v64, v60 offset0:64 offset1:80
	ds_write2_b32 v133, v65, v61 offset0:68 offset1:84
	ds_write2_b32 v132, v66, v62 offset0:72 offset1:88
	ds_write2_b32 v0, v67, v63 offset0:76 offset1:92
	s_waitcnt lgkmcnt(0)
	s_barrier
	v_add_u32_e32 v236, -4, v2
	v_ashrrev_i32_e32 v237, 31, v236
	v_lshlrev_b64 v[236:237], 10, v[236:237]
	v_lshl_add_u64 v[236:237], v[236:237], 0, v[198:199]
	v_lshlrev_b64 v[236:237], 1, v[236:237]
	v_lshl_add_u64 v[236:237], s[8:9], 0, v[236:237]
	global_load_dwordx4 v[148:151], v[236:237], off
	v_add_u32_e32 v236, 0, v2
	v_ashrrev_i32_e32 v237, 31, v236
	v_lshlrev_b64 v[236:237], 10, v[236:237]
	v_lshl_add_u64 v[236:237], v[236:237], 0, v[198:199]
	v_lshlrev_b64 v[236:237], 1, v[236:237]
	v_lshl_add_u64 v[236:237], s[8:9], 0, v[236:237]
	global_load_dwordx4 v[152:155], v[236:237], off
	v_add_u32_e32 v236, 4, v2
	v_ashrrev_i32_e32 v237, 31, v236
	v_lshlrev_b64 v[236:237], 10, v[236:237]
	v_lshl_add_u64 v[236:237], v[236:237], 0, v[198:199]
	v_lshlrev_b64 v[236:237], 1, v[236:237]
	v_lshl_add_u64 v[236:237], s[8:9], 0, v[236:237]
	global_load_dwordx4 v[156:159], v[236:237], off
	v_add_u32_e32 v236, 8, v2
	v_ashrrev_i32_e32 v237, 31, v236
	v_lshlrev_b64 v[236:237], 10, v[236:237]
	v_lshl_add_u64 v[236:237], v[236:237], 0, v[198:199]
	v_lshlrev_b64 v[236:237], 1, v[236:237]
	v_lshl_add_u64 v[236:237], s[8:9], 0, v[236:237]
	global_load_dwordx4 v[160:163], v[236:237], off
	v_add_u32_e32 v236, 12, v2
	v_ashrrev_i32_e32 v237, 31, v236
	v_lshlrev_b64 v[236:237], 10, v[236:237]
	v_lshl_add_u64 v[236:237], v[236:237], 0, v[198:199]
	v_lshlrev_b64 v[236:237], 1, v[236:237]
	v_lshl_add_u64 v[236:237], s[8:9], 0, v[236:237]
	global_load_dwordx4 v[164:167], v[236:237], off
	v_add_u32_e32 v236, 16, v2
	v_ashrrev_i32_e32 v237, 31, v236
	v_lshlrev_b64 v[236:237], 10, v[236:237]
	v_lshl_add_u64 v[236:237], v[236:237], 0, v[198:199]
	v_lshlrev_b64 v[236:237], 1, v[236:237]
	v_lshl_add_u64 v[236:237], s[8:9], 0, v[236:237]
	global_load_dwordx4 v[168:171], v[236:237], off
	v_add_u32_e32 v236, 20, v2
	v_ashrrev_i32_e32 v237, 31, v236
	v_lshlrev_b64 v[236:237], 10, v[236:237]
	v_lshl_add_u64 v[236:237], v[236:237], 0, v[198:199]
	v_lshlrev_b64 v[236:237], 1, v[236:237]
	v_lshl_add_u64 v[236:237], s[8:9], 0, v[236:237]
	global_load_dwordx4 v[172:175], v[236:237], off
	v_add_u32_e32 v236, 24, v2
	v_ashrrev_i32_e32 v237, 31, v236
	v_lshlrev_b64 v[236:237], 10, v[236:237]
	v_lshl_add_u64 v[236:237], v[236:237], 0, v[198:199]
	v_lshlrev_b64 v[236:237], 1, v[236:237]
	v_lshl_add_u64 v[236:237], s[8:9], 0, v[236:237]
	global_load_dwordx4 v[176:179], v[236:237], off
	ds_read_b128 v[180:183], v221 offset:0
	ds_read_b128 v[184:187], v221 offset:16
	v_add_u32_e32 v238, -4, v2
	v_ashrrev_i32_e32 v239, 31, v238
	v_lshlrev_b64 v[238:239], 10, v[238:239]
	v_lshl_add_u64 v[238:239], v[238:239], 0, v[198:199]
	v_lshlrev_b64 v[238:239], 1, v[238:239]
	v_lshl_add_u64 v[238:239], s[38:39], 0, v[238:239]
	s_waitcnt vmcnt(7)
	v_lshlrev_b32_e32 v200, 16, v148
	v_and_b32_e32 v201, 0xffff0000, v148
	v_lshlrev_b32_e32 v202, 16, v149
	v_and_b32_e32 v203, 0xffff0000, v149
	v_lshlrev_b32_e32 v204, 16, v150
	v_and_b32_e32 v205, 0xffff0000, v150
	v_lshlrev_b32_e32 v206, 16, v151
	v_and_b32_e32 v207, 0xffff0000, v151
	v_max_f32_e32 v200, v200, v200
	v_max_f32_e32 v201, v201, v201
	v_max_f32_e32 v202, v202, v202
	v_max_f32_e32 v203, v203, v203
	v_max_f32_e32 v204, v204, v204
	v_max_f32_e32 v205, v205, v205
	v_max_f32_e32 v206, v206, v206
	v_max_f32_e32 v207, v207, v207
	v_max_f32_e32 v200, 0xda24260, v200
	v_max_f32_e32 v201, 0xda24260, v201
	v_max_f32_e32 v202, 0xda24260, v202
	v_max_f32_e32 v203, 0xda24260, v203
	v_max_f32_e32 v204, 0xda24260, v204
	v_max_f32_e32 v205, 0xda24260, v205
	v_max_f32_e32 v206, 0xda24260, v206
	v_max_f32_e32 v207, 0xda24260, v207
	s_waitcnt lgkmcnt(0)
	v_pk_mul_f32 v[180:181], v[180:181], v[200:201]
	v_pk_mul_f32 v[182:183], v[182:183], v[202:203]
	v_pk_mul_f32 v[184:185], v[184:185], v[204:205]
	v_pk_mul_f32 v[186:187], v[186:187], v[206:207]
	v_cvt_pk_bf16_f32 v180, v180, v181
	v_cvt_pk_bf16_f32 v181, v182, v183
	v_cvt_pk_bf16_f32 v182, v184, v185
	v_cvt_pk_bf16_f32 v183, v186, v187
	global_store_dwordx4 v[238:239], v[180:183], off
	ds_read_b128 v[188:191], v221 offset:4160
	ds_read_b128 v[192:195], v221 offset:4176
	v_add_u32_e32 v240, 0, v2
	v_ashrrev_i32_e32 v241, 31, v240
	v_lshlrev_b64 v[240:241], 10, v[240:241]
	v_lshl_add_u64 v[240:241], v[240:241], 0, v[198:199]
	v_lshlrev_b64 v[240:241], 1, v[240:241]
	v_lshl_add_u64 v[240:241], s[38:39], 0, v[240:241]
	s_waitcnt vmcnt(7)
	v_lshlrev_b32_e32 v228, 16, v152
	v_and_b32_e32 v229, 0xffff0000, v152
	v_lshlrev_b32_e32 v230, 16, v153
	v_and_b32_e32 v231, 0xffff0000, v153
	v_lshlrev_b32_e32 v232, 16, v154
	v_and_b32_e32 v233, 0xffff0000, v154
	v_lshlrev_b32_e32 v234, 16, v155
	v_and_b32_e32 v235, 0xffff0000, v155
	v_max_f32_e32 v228, v228, v228
	v_max_f32_e32 v229, v229, v229
	v_max_f32_e32 v230, v230, v230
	v_max_f32_e32 v231, v231, v231
	v_max_f32_e32 v232, v232, v232
	v_max_f32_e32 v233, v233, v233
	v_max_f32_e32 v234, v234, v234
	v_max_f32_e32 v235, v235, v235
	v_max_f32_e32 v228, 0xda24260, v228
	v_max_f32_e32 v229, 0xda24260, v229
	v_max_f32_e32 v230, 0xda24260, v230
	v_max_f32_e32 v231, 0xda24260, v231
	v_max_f32_e32 v232, 0xda24260, v232
	v_max_f32_e32 v233, 0xda24260, v233
	v_max_f32_e32 v234, 0xda24260, v234
	v_max_f32_e32 v235, 0xda24260, v235
	s_waitcnt lgkmcnt(0)
	v_pk_mul_f32 v[188:189], v[188:189], v[228:229]
	v_pk_mul_f32 v[190:191], v[190:191], v[230:231]
	v_pk_mul_f32 v[192:193], v[192:193], v[232:233]
	v_pk_mul_f32 v[194:195], v[194:195], v[234:235]
	v_cvt_pk_bf16_f32 v188, v188, v189
	v_cvt_pk_bf16_f32 v189, v190, v191
	v_cvt_pk_bf16_f32 v190, v192, v193
	v_cvt_pk_bf16_f32 v191, v194, v195
	global_store_dwordx4 v[240:241], v[188:191], off
	ds_read_b128 v[180:183], v221 offset:8320
	ds_read_b128 v[184:187], v221 offset:8336
	v_add_u32_e32 v238, 4, v2
	v_ashrrev_i32_e32 v239, 31, v238
	v_lshlrev_b64 v[238:239], 10, v[238:239]
	v_lshl_add_u64 v[238:239], v[238:239], 0, v[198:199]
	v_lshlrev_b64 v[238:239], 1, v[238:239]
	v_lshl_add_u64 v[238:239], s[38:39], 0, v[238:239]
	s_waitcnt vmcnt(7)
	v_lshlrev_b32_e32 v200, 16, v156
	v_and_b32_e32 v201, 0xffff0000, v156
	v_lshlrev_b32_e32 v202, 16, v157
	v_and_b32_e32 v203, 0xffff0000, v157
	v_lshlrev_b32_e32 v204, 16, v158
	v_and_b32_e32 v205, 0xffff0000, v158
	v_lshlrev_b32_e32 v206, 16, v159
	v_and_b32_e32 v207, 0xffff0000, v159
	v_max_f32_e32 v200, v200, v200
	v_max_f32_e32 v201, v201, v201
	v_max_f32_e32 v202, v202, v202
	v_max_f32_e32 v203, v203, v203
	v_max_f32_e32 v204, v204, v204
	v_max_f32_e32 v205, v205, v205
	v_max_f32_e32 v206, v206, v206
	v_max_f32_e32 v207, v207, v207
	v_max_f32_e32 v200, 0xda24260, v200
	v_max_f32_e32 v201, 0xda24260, v201
	v_max_f32_e32 v202, 0xda24260, v202
	v_max_f32_e32 v203, 0xda24260, v203
	v_max_f32_e32 v204, 0xda24260, v204
	v_max_f32_e32 v205, 0xda24260, v205
	v_max_f32_e32 v206, 0xda24260, v206
	v_max_f32_e32 v207, 0xda24260, v207
	s_waitcnt lgkmcnt(0)
	v_pk_mul_f32 v[180:181], v[180:181], v[200:201]
	v_pk_mul_f32 v[182:183], v[182:183], v[202:203]
	v_pk_mul_f32 v[184:185], v[184:185], v[204:205]
	v_pk_mul_f32 v[186:187], v[186:187], v[206:207]
	v_cvt_pk_bf16_f32 v180, v180, v181
	v_cvt_pk_bf16_f32 v181, v182, v183
	v_cvt_pk_bf16_f32 v182, v184, v185
	v_cvt_pk_bf16_f32 v183, v186, v187
	global_store_dwordx4 v[238:239], v[180:183], off
	ds_read_b128 v[188:191], v221 offset:12480
	ds_read_b128 v[192:195], v221 offset:12496
	v_add_u32_e32 v240, 8, v2
	v_ashrrev_i32_e32 v241, 31, v240
	v_lshlrev_b64 v[240:241], 10, v[240:241]
	v_lshl_add_u64 v[240:241], v[240:241], 0, v[198:199]
	v_lshlrev_b64 v[240:241], 1, v[240:241]
	v_lshl_add_u64 v[240:241], s[38:39], 0, v[240:241]
	s_waitcnt vmcnt(7)
	v_lshlrev_b32_e32 v228, 16, v160
	v_and_b32_e32 v229, 0xffff0000, v160
	v_lshlrev_b32_e32 v230, 16, v161
	v_and_b32_e32 v231, 0xffff0000, v161
	v_lshlrev_b32_e32 v232, 16, v162
	v_and_b32_e32 v233, 0xffff0000, v162
	v_lshlrev_b32_e32 v234, 16, v163
	v_and_b32_e32 v235, 0xffff0000, v163
	v_max_f32_e32 v228, v228, v228
	v_max_f32_e32 v229, v229, v229
	v_max_f32_e32 v230, v230, v230
	v_max_f32_e32 v231, v231, v231
	v_max_f32_e32 v232, v232, v232
	v_max_f32_e32 v233, v233, v233
	v_max_f32_e32 v234, v234, v234
	v_max_f32_e32 v235, v235, v235
	v_max_f32_e32 v228, 0xda24260, v228
	v_max_f32_e32 v229, 0xda24260, v229
	v_max_f32_e32 v230, 0xda24260, v230
	v_max_f32_e32 v231, 0xda24260, v231
	v_max_f32_e32 v232, 0xda24260, v232
	v_max_f32_e32 v233, 0xda24260, v233
	v_max_f32_e32 v234, 0xda24260, v234
	v_max_f32_e32 v235, 0xda24260, v235
	s_waitcnt lgkmcnt(0)
	v_pk_mul_f32 v[188:189], v[188:189], v[228:229]
	v_pk_mul_f32 v[190:191], v[190:191], v[230:231]
	v_pk_mul_f32 v[192:193], v[192:193], v[232:233]
	v_pk_mul_f32 v[194:195], v[194:195], v[234:235]
	v_cvt_pk_bf16_f32 v188, v188, v189
	v_cvt_pk_bf16_f32 v189, v190, v191
	v_cvt_pk_bf16_f32 v190, v192, v193
	v_cvt_pk_bf16_f32 v191, v194, v195
	global_store_dwordx4 v[240:241], v[188:191], off
	ds_read_b128 v[180:183], v221 offset:16640
	ds_read_b128 v[184:187], v221 offset:16656
	v_add_u32_e32 v238, 12, v2
	v_ashrrev_i32_e32 v239, 31, v238
	v_lshlrev_b64 v[238:239], 10, v[238:239]
	v_lshl_add_u64 v[238:239], v[238:239], 0, v[198:199]
	v_lshlrev_b64 v[238:239], 1, v[238:239]
	v_lshl_add_u64 v[238:239], s[38:39], 0, v[238:239]
	s_waitcnt vmcnt(7)
	v_lshlrev_b32_e32 v200, 16, v164
	v_and_b32_e32 v201, 0xffff0000, v164
	v_lshlrev_b32_e32 v202, 16, v165
	v_and_b32_e32 v203, 0xffff0000, v165
	v_lshlrev_b32_e32 v204, 16, v166
	v_and_b32_e32 v205, 0xffff0000, v166
	v_lshlrev_b32_e32 v206, 16, v167
	v_and_b32_e32 v207, 0xffff0000, v167
	v_max_f32_e32 v200, v200, v200
	v_max_f32_e32 v201, v201, v201
	v_max_f32_e32 v202, v202, v202
	v_max_f32_e32 v203, v203, v203
	v_max_f32_e32 v204, v204, v204
	v_max_f32_e32 v205, v205, v205
	v_max_f32_e32 v206, v206, v206
	v_max_f32_e32 v207, v207, v207
	v_max_f32_e32 v200, 0xda24260, v200
	v_max_f32_e32 v201, 0xda24260, v201
	v_max_f32_e32 v202, 0xda24260, v202
	v_max_f32_e32 v203, 0xda24260, v203
	v_max_f32_e32 v204, 0xda24260, v204
	v_max_f32_e32 v205, 0xda24260, v205
	v_max_f32_e32 v206, 0xda24260, v206
	v_max_f32_e32 v207, 0xda24260, v207
	s_waitcnt lgkmcnt(0)
	v_pk_mul_f32 v[180:181], v[180:181], v[200:201]
	v_pk_mul_f32 v[182:183], v[182:183], v[202:203]
	v_pk_mul_f32 v[184:185], v[184:185], v[204:205]
	v_pk_mul_f32 v[186:187], v[186:187], v[206:207]
	v_cvt_pk_bf16_f32 v180, v180, v181
	v_cvt_pk_bf16_f32 v181, v182, v183
	v_cvt_pk_bf16_f32 v182, v184, v185
	v_cvt_pk_bf16_f32 v183, v186, v187
	global_store_dwordx4 v[238:239], v[180:183], off
	ds_read_b128 v[188:191], v221 offset:20800
	ds_read_b128 v[192:195], v221 offset:20816
	v_add_u32_e32 v240, 16, v2
	v_ashrrev_i32_e32 v241, 31, v240
	v_lshlrev_b64 v[240:241], 10, v[240:241]
	v_lshl_add_u64 v[240:241], v[240:241], 0, v[198:199]
	v_lshlrev_b64 v[240:241], 1, v[240:241]
	v_lshl_add_u64 v[240:241], s[38:39], 0, v[240:241]
	s_waitcnt vmcnt(7)
	v_lshlrev_b32_e32 v228, 16, v168
	v_and_b32_e32 v229, 0xffff0000, v168
	v_lshlrev_b32_e32 v230, 16, v169
	v_and_b32_e32 v231, 0xffff0000, v169
	v_lshlrev_b32_e32 v232, 16, v170
	v_and_b32_e32 v233, 0xffff0000, v170
	v_lshlrev_b32_e32 v234, 16, v171
	v_and_b32_e32 v235, 0xffff0000, v171
	v_max_f32_e32 v228, v228, v228
	v_max_f32_e32 v229, v229, v229
	v_max_f32_e32 v230, v230, v230
	v_max_f32_e32 v231, v231, v231
	v_max_f32_e32 v232, v232, v232
	v_max_f32_e32 v233, v233, v233
	v_max_f32_e32 v234, v234, v234
	v_max_f32_e32 v235, v235, v235
	v_max_f32_e32 v228, 0xda24260, v228
	v_max_f32_e32 v229, 0xda24260, v229
	v_max_f32_e32 v230, 0xda24260, v230
	v_max_f32_e32 v231, 0xda24260, v231
	v_max_f32_e32 v232, 0xda24260, v232
	v_max_f32_e32 v233, 0xda24260, v233
	v_max_f32_e32 v234, 0xda24260, v234
	v_max_f32_e32 v235, 0xda24260, v235
	s_waitcnt lgkmcnt(0)
	v_pk_mul_f32 v[188:189], v[188:189], v[228:229]
	v_pk_mul_f32 v[190:191], v[190:191], v[230:231]
	v_pk_mul_f32 v[192:193], v[192:193], v[232:233]
	v_pk_mul_f32 v[194:195], v[194:195], v[234:235]
	v_cvt_pk_bf16_f32 v188, v188, v189
	v_cvt_pk_bf16_f32 v189, v190, v191
	v_cvt_pk_bf16_f32 v190, v192, v193
	v_cvt_pk_bf16_f32 v191, v194, v195
	global_store_dwordx4 v[240:241], v[188:191], off
	ds_read_b128 v[180:183], v221 offset:24960
	ds_read_b128 v[184:187], v221 offset:24976
	v_add_u32_e32 v238, 20, v2
	v_ashrrev_i32_e32 v239, 31, v238
	v_lshlrev_b64 v[238:239], 10, v[238:239]
	v_lshl_add_u64 v[238:239], v[238:239], 0, v[198:199]
	v_lshlrev_b64 v[238:239], 1, v[238:239]
	v_lshl_add_u64 v[238:239], s[38:39], 0, v[238:239]
	s_waitcnt vmcnt(7)
	v_lshlrev_b32_e32 v200, 16, v172
	v_and_b32_e32 v201, 0xffff0000, v172
	v_lshlrev_b32_e32 v202, 16, v173
	v_and_b32_e32 v203, 0xffff0000, v173
	v_lshlrev_b32_e32 v204, 16, v174
	v_and_b32_e32 v205, 0xffff0000, v174
	v_lshlrev_b32_e32 v206, 16, v175
	v_and_b32_e32 v207, 0xffff0000, v175
	v_max_f32_e32 v200, v200, v200
	v_max_f32_e32 v201, v201, v201
	v_max_f32_e32 v202, v202, v202
	v_max_f32_e32 v203, v203, v203
	v_max_f32_e32 v204, v204, v204
	v_max_f32_e32 v205, v205, v205
	v_max_f32_e32 v206, v206, v206
	v_max_f32_e32 v207, v207, v207
	v_max_f32_e32 v200, 0xda24260, v200
	v_max_f32_e32 v201, 0xda24260, v201
	v_max_f32_e32 v202, 0xda24260, v202
	v_max_f32_e32 v203, 0xda24260, v203
	v_max_f32_e32 v204, 0xda24260, v204
	v_max_f32_e32 v205, 0xda24260, v205
	v_max_f32_e32 v206, 0xda24260, v206
	v_max_f32_e32 v207, 0xda24260, v207
	s_waitcnt lgkmcnt(0)
	v_pk_mul_f32 v[180:181], v[180:181], v[200:201]
	v_pk_mul_f32 v[182:183], v[182:183], v[202:203]
	v_pk_mul_f32 v[184:185], v[184:185], v[204:205]
	v_pk_mul_f32 v[186:187], v[186:187], v[206:207]
	v_cvt_pk_bf16_f32 v180, v180, v181
	v_cvt_pk_bf16_f32 v181, v182, v183
	v_cvt_pk_bf16_f32 v182, v184, v185
	v_cvt_pk_bf16_f32 v183, v186, v187
	global_store_dwordx4 v[238:239], v[180:183], off
	ds_read_b128 v[188:191], v221 offset:29120
	ds_read_b128 v[192:195], v221 offset:29136
	v_add_u32_e32 v240, 24, v2
	v_ashrrev_i32_e32 v241, 31, v240
	v_lshlrev_b64 v[240:241], 10, v[240:241]
	v_lshl_add_u64 v[240:241], v[240:241], 0, v[198:199]
	v_lshlrev_b64 v[240:241], 1, v[240:241]
	v_lshl_add_u64 v[240:241], s[38:39], 0, v[240:241]
	s_waitcnt vmcnt(7)
	v_lshlrev_b32_e32 v228, 16, v176
	v_and_b32_e32 v229, 0xffff0000, v176
	v_lshlrev_b32_e32 v230, 16, v177
	v_and_b32_e32 v231, 0xffff0000, v177
	v_lshlrev_b32_e32 v232, 16, v178
	v_and_b32_e32 v233, 0xffff0000, v178
	v_lshlrev_b32_e32 v234, 16, v179
	v_and_b32_e32 v235, 0xffff0000, v179
	v_max_f32_e32 v228, v228, v228
	v_max_f32_e32 v229, v229, v229
	v_max_f32_e32 v230, v230, v230
	v_max_f32_e32 v231, v231, v231
	v_max_f32_e32 v232, v232, v232
	v_max_f32_e32 v233, v233, v233
	v_max_f32_e32 v234, v234, v234
	v_max_f32_e32 v235, v235, v235
	v_max_f32_e32 v228, 0xda24260, v228
	v_max_f32_e32 v229, 0xda24260, v229
	v_max_f32_e32 v230, 0xda24260, v230
	v_max_f32_e32 v231, 0xda24260, v231
	v_max_f32_e32 v232, 0xda24260, v232
	v_max_f32_e32 v233, 0xda24260, v233
	v_max_f32_e32 v234, 0xda24260, v234
	v_max_f32_e32 v235, 0xda24260, v235
	s_waitcnt lgkmcnt(0)
	v_pk_mul_f32 v[188:189], v[188:189], v[228:229]
	v_pk_mul_f32 v[190:191], v[190:191], v[230:231]
	v_pk_mul_f32 v[192:193], v[192:193], v[232:233]
	v_pk_mul_f32 v[194:195], v[194:195], v[234:235]
	v_cvt_pk_bf16_f32 v188, v188, v189
	v_cvt_pk_bf16_f32 v189, v190, v191
	v_cvt_pk_bf16_f32 v190, v192, v193
	v_cvt_pk_bf16_f32 v191, v194, v195
	global_store_dwordx4 v[240:241], v[188:191], off
